# grid barrier: L1 invalidate issued and completed before the arrival atomic (no cacheable loads between it and the release), none after release
# speedup vs baseline: 1.0247x; 1.0247x over previous
.LBB0_9:
	s_or_b64 exec, exec, s[2:3]
	v_readlane_b32 s2, v252, 39
	v_readlane_b32 s3, v252, 40
	v_mov_b32_e32 v2, 1
	s_waitcnt vmcnt(0)
	s_nop 1
	s_nop 1
	global_atomic_add v3, v2, s[2:3]
	s_waitcnt vmcnt(0)

.LBB0_732:
	v_readlane_b32 s0, v251, 3
	v_readlane_b32 s1, v251, 4
	s_add_i32 s0, s0, 1
	v_writelane_b32 v251, s0, 3
	s_cmp_ge_i32 s0, s1
	s_nop 0
	v_writelane_b32 v251, s1, 4
	s_mov_b64 s[0:1], -1
	s_cbranch_scc1 .Ltramp_LBB0_11
	s_waitcnt vmcnt(0)
	s_barrier
	s_mov_b64 s[0:1], exec
	v_readlane_b32 s2, v252, 58
	v_readlane_b32 s3, v252, 59
	s_and_b64 s[2:3], s[0:1], s[2:3]
	s_mov_b64 exec, s[2:3]
	s_cbranch_execz .Ltramp_LBB0_10
	v_mov_b32_e32 v2, 0x12000
	s_waitcnt vmcnt(0) expcnt(0) lgkmcnt(0)
	buffer_inv sc1
	s_waitcnt vmcnt(0)
	ds_read_b32 v5, v2
	v_mov_b32_e32 v2, 0x12004
	ds_read_b32 v4, v2
	s_waitcnt lgkmcnt(1)
	v_cmp_ne_u32_e32 vcc, 0, v5
	s_cbranch_vccnz .LBB0_749
	s_load_dwordx2 s[2:3], s[62:63], 0x0
	s_load_dword s4, s[62:63], 0x8
	s_mov_b32 s9, 1
	s_waitcnt lgkmcnt(0)
	s_mul_i32 s8, s3, s2
	s_mul_i32 s8, s8, s4
	s_branch .LBB0_737

.LBB0_762:
	s_or_b64 exec, exec, s[4:5]
	s_waitcnt vmcnt(0)
	s_waitcnt vmcnt(0)
